# P6: the 48 out-of-round workgroups leave the grid-stride conv-state copies to the other 208
# speedup vs baseline: 1.0055x; 1.0055x over previous
.Lt5_p6:
	v_readlane_b32 s0, v239, 2
	s_waitcnt lgkmcnt(0)
	v_mov_b32_e32 v0, v176
	s_barrier
	s_mov_b32 s22, 0x1a000
	s_mov_b32 s0, 0x18c00
	v_add_u32_e32 v144, s96, v0
	s_cmp_eq_u32 s97, 2
	s_cbranch_scc1 .Lt5_own
	s_mov_b32 s4, 0x2e8ba2e9
	v_mul_hi_i32 v1, v144, s4
	v_lshrrev_b32_e32 v2, 31, v1
	v_ashrrev_i32_e32 v1, 7, v1
	v_add_u32_e32 v1, v1, v2
	v_mul_i32_i24_e32 v2, 0x2c0, v1
	v_sub_u32_e32 v2, v144, v2
	s_movk_i32 s6, 0x13f
	v_cmp_lt_u32_e32 vcc, 0x7f, v1
	v_cmp_lt_u32_e64 s[4:5], s6, v2
	v_mov_b32_e32 v1, 0x7fffffff
	s_nop 1
	s_and_b64 vcc, vcc, s[4:5]
	s_nop 1
	v_cndmask_b32_e32 v144, v144, v1, vcc
	s_branch .Lt5_tasks

.Lsffn2_loop:
	s_mov_b64 s[6:7], exec
	v_cmp_gt_u32_e64 s[8:9], s5, v0
	v_lshrrev_b32_e32 v12, 7, v0
	v_mul_hi_u32 v12, v12, s4
	v_lshrrev_b32_e32 v12, 3, v12
	v_mul_u32_u24_e32 v13, 0x580, v12
	v_sub_u32_e32 v13, v0, v13
	v_and_b32_e32 v14, 1, v12
	v_sub_u32_e32 v4, v12, v14
	v_lshl_add_u32 v4, v4, 2, v14
	v_add_u32_e32 v4, 0x2006, v4
	v_mul_u32_u24_e32 v4, 0x5800, v4
	v_lshl_add_u32 v4, v13, 4, v4
	v_mul_u32_u24_e32 v8, 0xb000, v12
	v_lshl_add_u32 v8, v13, 5, v8
	v_add_u32_e32 v8, 0xd13e840, v8
	v_add_u32_e32 v1, s16, v0
	v_cmp_gt_u32_e64 s[10:11], s5, v1
	v_lshrrev_b32_e32 v12, 7, v1
	v_mul_hi_u32 v12, v12, s4
	v_lshrrev_b32_e32 v12, 3, v12
	v_mul_u32_u24_e32 v13, 0x580, v12
	v_sub_u32_e32 v13, v1, v13
	v_and_b32_e32 v14, 1, v12
	v_sub_u32_e32 v5, v12, v14
	v_lshl_add_u32 v5, v5, 2, v14
	v_add_u32_e32 v5, 0x2006, v5
	v_mul_u32_u24_e32 v5, 0x5800, v5
	v_lshl_add_u32 v5, v13, 4, v5
	v_mul_u32_u24_e32 v9, 0xb000, v12
	v_lshl_add_u32 v9, v13, 5, v9
	v_add_u32_e32 v9, 0xd13e840, v9
	v_add_u32_e32 v2, s16, v1
	v_cmp_gt_u32_e64 s[12:13], s5, v2
	v_lshrrev_b32_e32 v12, 7, v2
	v_mul_hi_u32 v12, v12, s4
	v_lshrrev_b32_e32 v12, 3, v12
	v_mul_u32_u24_e32 v13, 0x580, v12
	v_sub_u32_e32 v13, v2, v13
	v_and_b32_e32 v14, 1, v12
	v_sub_u32_e32 v6, v12, v14
	v_lshl_add_u32 v6, v6, 2, v14
	v_add_u32_e32 v6, 0x2006, v6
	v_mul_u32_u24_e32 v6, 0x5800, v6
	v_lshl_add_u32 v6, v13, 4, v6
	v_mul_u32_u24_e32 v10, 0xb000, v12
	v_lshl_add_u32 v10, v13, 5, v10
	v_add_u32_e32 v10, 0xd13e840, v10
	v_add_u32_e32 v3, s16, v2
	v_cmp_gt_u32_e64 s[14:15], s5, v3
	v_lshrrev_b32_e32 v12, 7, v3
	v_mul_hi_u32 v12, v12, s4
	v_lshrrev_b32_e32 v12, 3, v12
	v_mul_u32_u24_e32 v13, 0x580, v12
	v_sub_u32_e32 v13, v3, v13
	v_and_b32_e32 v14, 1, v12
	v_sub_u32_e32 v7, v12, v14
	v_lshl_add_u32 v7, v7, 2, v14
	v_add_u32_e32 v7, 0x2006, v7
	v_mul_u32_u24_e32 v7, 0x5800, v7
	v_lshl_add_u32 v7, v13, 4, v7
	v_mul_u32_u24_e32 v11, 0xb000, v12
	v_lshl_add_u32 v11, v13, 5, v11
	v_add_u32_e32 v11, 0xd13e840, v11
	s_and_b64 exec, s[6:7], s[8:9]
	global_load_dwordx4 v[240:243], v4, s[30:31]
	s_and_b64 exec, s[6:7], s[10:11]
	global_load_dwordx4 v[244:247], v5, s[30:31]
	s_and_b64 exec, s[6:7], s[12:13]
	global_load_dwordx4 v[248:251], v6, s[30:31]
	s_and_b64 exec, s[6:7], s[14:15]
	global_load_dwordx4 v[252:255], v7, s[30:31]
	s_waitcnt vmcnt(0)
	s_and_b64 exec, s[6:7], s[8:9]
	v_lshlrev_b32_e32 v12, 16, v240
	v_and_b32_e32 v13, 0xffff0000, v240
	v_lshlrev_b32_e32 v14, 16, v241
	v_and_b32_e32 v15, 0xffff0000, v241
	global_store_dwordx4 v8, v[12:15], s[28:29]
	v_lshlrev_b32_e32 v240, 16, v242
	v_and_b32_e32 v241, 0xffff0000, v242
	v_lshlrev_b32_e32 v242, 16, v243
	v_and_b32_e32 v243, 0xffff0000, v243
	global_store_dwordx4 v8, v[240:243], s[28:29] offset:16
	s_nop 1
	s_and_b64 exec, s[6:7], s[10:11]
	v_lshlrev_b32_e32 v12, 16, v244
	v_and_b32_e32 v13, 0xffff0000, v244
	v_lshlrev_b32_e32 v14, 16, v245
	v_and_b32_e32 v15, 0xffff0000, v245
	global_store_dwordx4 v9, v[12:15], s[28:29]
	v_lshlrev_b32_e32 v244, 16, v246
	v_and_b32_e32 v245, 0xffff0000, v246
	v_lshlrev_b32_e32 v246, 16, v247
	v_and_b32_e32 v247, 0xffff0000, v247
	global_store_dwordx4 v9, v[244:247], s[28:29] offset:16
	s_nop 1
	s_and_b64 exec, s[6:7], s[12:13]
	v_lshlrev_b32_e32 v12, 16, v248
	v_and_b32_e32 v13, 0xffff0000, v248
	v_lshlrev_b32_e32 v14, 16, v249
	v_and_b32_e32 v15, 0xffff0000, v249
	global_store_dwordx4 v10, v[12:15], s[28:29]
	v_lshlrev_b32_e32 v248, 16, v250
	v_and_b32_e32 v249, 0xffff0000, v250
	v_lshlrev_b32_e32 v250, 16, v251
	v_and_b32_e32 v251, 0xffff0000, v251
	global_store_dwordx4 v10, v[248:251], s[28:29] offset:16
	s_nop 1
	s_and_b64 exec, s[6:7], s[14:15]
	v_lshlrev_b32_e32 v12, 16, v252
	v_and_b32_e32 v13, 0xffff0000, v252
	v_lshlrev_b32_e32 v14, 16, v253
	v_and_b32_e32 v15, 0xffff0000, v253
	global_store_dwordx4 v11, v[12:15], s[28:29]
	v_lshlrev_b32_e32 v252, 16, v254
	v_and_b32_e32 v253, 0xffff0000, v254
	v_lshlrev_b32_e32 v254, 16, v255
	v_and_b32_e32 v255, 0xffff0000, v255
	global_store_dwordx4 v11, v[252:255], s[28:29] offset:16
	s_nop 1
	s_mov_b64 exec, s[6:7]
	v_add_u32_e32 v0, s16, v3
	v_cmp_gt_u32_e32 vcc, s5, v0
	s_and_b64 exec, exec, vcc
	s_cbranch_execnz .Lsffn2_loop
	s_mov_b64 exec, s[18:19]
	v_mov_b32_e32 v144, 0x7fffffff
